# FFN1 tile-epilogue head barrier dropped (double-buffered LDS-DMA makes it redundant) on top of paired-store FFN1 epilogue
# speedup vs baseline: 1.0036x; 1.0012x over previous
; DI int TIDX() { int t = threadIdx.x; asm volatile("" : "+v"(t)); return t; }
; DI float sigmoidf_(float x) { return __builtin_amdgcn_rcpf(1.f + __expf(-x)); }
; DI void phase_ffn1(const P& p, int l, int hf, char* smem) {
;     ...
;     const int lane = TIDX() & 63, w = TIDX() >> 6, wm = w >> 1, wn = w & 1, hh = lane >> 5, c = lane & 31;
;     const int ml0 = m0 - mt0 * 128;
; #pragma unroll
;     for (int mi = 0; mi < 4; ++mi) {
;       const int rbase = ml0 + wm * 128 + mi * 32 + 4 * hh, n = c0 + wn * 32 + c;
; #pragma unroll
;       for (int i = 0; i < 16; ++i) {
;         const float g = acc[mi][0][i];
;         act[(size_t)EROW(rbase, i) * 2816 + n] = (h16)(g * sigmoidf_(g) * acc[mi][1][i]);
;       }
;     }
.LBB0_69:
	v_mov_b32_e32 v0, v203
	v_mov_b32_e32 v130, v203
	s_nop 7
	s_nop 7
	s_nop 7
	s_movk_i32 s2, 0x1600
	v_and_b32_e32 v132, 0xffffff80, v203
	v_add_u32_e32 v132, s12, v132
	v_lshrrev_b32_e32 v133, 3, v203
	v_and_or_b32 v132, v133, 4, v132
	v_and_b32_e32 v131, 31, v203
	v_lshrrev_b32_e32 v130, 1, v203
	v_and_b32_e32 v130, 32, v130
	v_or3_b32 v130, v131, v130, s26
	v_and_b32_e32 v133, 1, v130
	v_add_u32_e32 v132, v132, v133
	v_and_b32_e32 v130, -2, v130
	v_lshlrev_b32_e32 v130, 1, v130
	v_mad_u32_u24 v130, v132, s2, v130
	v_mov_b32_e32 v194, 0x05040100
	v_mov_b32_e32 v131, 0x03020706
	v_cmp_eq_u32_e64 s[12:13], 1, v133
	s_nop 1
	v_cndmask_b32_e64 v194, v194, v131, s[12:13]
	v_mul_f32_e32 v178, 0xbfb8aa3b, v114
	v_mul_f32_e32 v179, 0xbfb8aa3b, v115
	v_mul_f32_e32 v180, 0xbfb8aa3b, v116
	v_mul_f32_e32 v181, 0xbfb8aa3b, v117
	v_mul_f32_e32 v182, 0xbfb8aa3b, v118
	v_mul_f32_e32 v183, 0xbfb8aa3b, v119
	v_mul_f32_e32 v184, 0xbfb8aa3b, v120
	v_mul_f32_e32 v185, 0xbfb8aa3b, v121
	v_exp_f32_e32 v178, v178
	v_exp_f32_e32 v179, v179
	v_exp_f32_e32 v180, v180
	v_exp_f32_e32 v181, v181
	v_exp_f32_e32 v182, v182
	v_exp_f32_e32 v183, v183
	v_exp_f32_e32 v184, v184
	v_exp_f32_e32 v185, v185
	v_mov_b32_e32 v190, v130
	v_add_u32_e32 v191, 0x2c00, v130
	v_add_u32_e32 v192, 0xb000, v130
	v_add_u32_e32 v193, 0xdc00, v130
	v_add_f32_e32 v178, 1.0, v178
	v_add_f32_e32 v179, 1.0, v179
	v_add_f32_e32 v180, 1.0, v180
	v_add_f32_e32 v181, 1.0, v181
	v_add_f32_e32 v182, 1.0, v182
	v_add_f32_e32 v183, 1.0, v183
	v_add_f32_e32 v184, 1.0, v184
	v_add_f32_e32 v185, 1.0, v185
	v_rcp_f32_e32 v178, v178
	v_rcp_f32_e32 v179, v179
	v_rcp_f32_e32 v180, v180
	v_rcp_f32_e32 v181, v181
	v_rcp_f32_e32 v182, v182
	v_rcp_f32_e32 v183, v183
	v_rcp_f32_e32 v184, v184
	v_rcp_f32_e32 v185, v185
	v_mul_f32_e32 v178, v114, v178
	v_mul_f32_e32 v179, v115, v179
	v_mul_f32_e32 v180, v116, v180
	v_mul_f32_e32 v181, v117, v181
	v_mul_f32_e32 v182, v118, v182
	v_mul_f32_e32 v183, v119, v183
	v_mul_f32_e32 v184, v120, v184
	v_mul_f32_e32 v185, v121, v185
	v_fma_mixlo_f16 v178, v98, v178, 0
	v_fma_mixlo_f16 v180, v100, v180, 0
	v_fma_mixlo_f16 v182, v102, v182, 0
	v_fma_mixlo_f16 v184, v104, v184, 0
	v_fma_mixhi_f16 v178, v99, v179, 0
	v_fma_mixhi_f16 v180, v101, v181, 0
	v_fma_mixhi_f16 v182, v103, v183, 0
	v_fma_mixhi_f16 v184, v105, v185, 0
	v_mov_b32_dpp v186, v178 quad_perm:[1,0,3,2] row_mask:0xf bank_mask:0xf
	v_mov_b32_dpp v187, v180 quad_perm:[1,0,3,2] row_mask:0xf bank_mask:0xf
	v_mov_b32_dpp v188, v182 quad_perm:[1,0,3,2] row_mask:0xf bank_mask:0xf
	v_mov_b32_dpp v189, v184 quad_perm:[1,0,3,2] row_mask:0xf bank_mask:0xf
	v_perm_b32 v178, v186, v178, v194
	v_perm_b32 v180, v187, v180, v194
	v_perm_b32 v182, v188, v182, v194
	v_perm_b32 v184, v189, v184, v194
	global_store_dword v190, v178, s[8:9]
	global_store_dword v191, v180, s[8:9]
	global_store_dword v192, v182, s[8:9]
	global_store_dword v193, v184, s[8:9]
	v_mul_f32_e32 v178, 0xbfb8aa3b, v122
	v_mul_f32_e32 v179, 0xbfb8aa3b, v123
	v_mul_f32_e32 v180, 0xbfb8aa3b, v124
	v_mul_f32_e32 v181, 0xbfb8aa3b, v125
	v_mul_f32_e32 v182, 0xbfb8aa3b, v126
	v_mul_f32_e32 v183, 0xbfb8aa3b, v127
	v_mul_f32_e32 v184, 0xbfb8aa3b, v128
	v_mul_f32_e32 v185, 0xbfb8aa3b, v129
	v_exp_f32_e32 v178, v178
	v_exp_f32_e32 v179, v179
	v_exp_f32_e32 v180, v180
	v_exp_f32_e32 v181, v181
	v_exp_f32_e32 v182, v182
	v_exp_f32_e32 v183, v183
	v_exp_f32_e32 v184, v184
	v_exp_f32_e32 v185, v185
	v_add_u32_e32 v190, 0x16000, v130
	v_add_u32_e32 v191, 0x18c00, v130
	v_add_u32_e32 v192, 0x21000, v130
	v_add_u32_e32 v193, 0x23c00, v130
	v_add_f32_e32 v178, 1.0, v178
	v_add_f32_e32 v179, 1.0, v179
	v_add_f32_e32 v180, 1.0, v180
	v_add_f32_e32 v181, 1.0, v181
	v_add_f32_e32 v182, 1.0, v182
	v_add_f32_e32 v183, 1.0, v183
	v_add_f32_e32 v184, 1.0, v184
	v_add_f32_e32 v185, 1.0, v185
	v_rcp_f32_e32 v178, v178
	v_rcp_f32_e32 v179, v179
	v_rcp_f32_e32 v180, v180
	v_rcp_f32_e32 v181, v181
	v_rcp_f32_e32 v182, v182
	v_rcp_f32_e32 v183, v183
	v_rcp_f32_e32 v184, v184
	v_rcp_f32_e32 v185, v185
	v_mul_f32_e32 v178, v122, v178
	v_mul_f32_e32 v179, v123, v179
	v_mul_f32_e32 v180, v124, v180
	v_mul_f32_e32 v181, v125, v181
	v_mul_f32_e32 v182, v126, v182
	v_mul_f32_e32 v183, v127, v183
	v_mul_f32_e32 v184, v128, v184
	v_mul_f32_e32 v185, v129, v185
	v_fma_mixlo_f16 v178, v106, v178, 0
	v_fma_mixlo_f16 v180, v108, v180, 0
	v_fma_mixlo_f16 v182, v110, v182, 0
	v_fma_mixlo_f16 v184, v112, v184, 0
	v_fma_mixhi_f16 v178, v107, v179, 0
	v_fma_mixhi_f16 v180, v109, v181, 0
	v_fma_mixhi_f16 v182, v111, v183, 0
	v_fma_mixhi_f16 v184, v113, v185, 0
	v_mov_b32_dpp v186, v178 quad_perm:[1,0,3,2] row_mask:0xf bank_mask:0xf
	v_mov_b32_dpp v187, v180 quad_perm:[1,0,3,2] row_mask:0xf bank_mask:0xf
	v_mov_b32_dpp v188, v182 quad_perm:[1,0,3,2] row_mask:0xf bank_mask:0xf
	v_mov_b32_dpp v189, v184 quad_perm:[1,0,3,2] row_mask:0xf bank_mask:0xf
	v_perm_b32 v178, v186, v178, v194
	v_perm_b32 v180, v187, v180, v194
	v_perm_b32 v182, v188, v182, v194
	v_perm_b32 v184, v189, v184, v194
	global_store_dword v190, v178, s[8:9]
	global_store_dword v191, v180, s[8:9]
	global_store_dword v192, v182, s[8:9]
	global_store_dword v193, v184, s[8:9]
	v_mul_f32_e32 v178, 0xbfb8aa3b, v82
	v_mul_f32_e32 v179, 0xbfb8aa3b, v83
	v_mul_f32_e32 v180, 0xbfb8aa3b, v84
	v_mul_f32_e32 v181, 0xbfb8aa3b, v85
	v_mul_f32_e32 v182, 0xbfb8aa3b, v86
	v_mul_f32_e32 v183, 0xbfb8aa3b, v87
	v_mul_f32_e32 v184, 0xbfb8aa3b, v88
	v_mul_f32_e32 v185, 0xbfb8aa3b, v89
	v_exp_f32_e32 v178, v178
	v_exp_f32_e32 v179, v179
	v_exp_f32_e32 v180, v180
	v_exp_f32_e32 v181, v181
	v_exp_f32_e32 v182, v182
	v_exp_f32_e32 v183, v183
	v_exp_f32_e32 v184, v184
; DI int TIDX() { int t = threadIdx.x; asm volatile("" : "+v"(t)); return t; }
; DI float sigmoidf_(float x) { return __builtin_amdgcn_rcpf(1.f + __expf(-x)); }
; DI void phase_ffn1(const P& p, int l, int hf, char* smem) {
;     ...
;     const int lane = TIDX() & 63, w = TIDX() >> 6, wm = w >> 1, wn = w & 1, hh = lane >> 5, c = lane & 31;
;     const int ml0 = m0 - mt0 * 128;
; #pragma unroll
;     for (int mi = 0; mi < 4; ++mi) {
;       const int rbase = ml0 + wm * 128 + mi * 32 + 4 * hh, n = c0 + wn * 32 + c;
; #pragma unroll
;       for (int i = 0; i < 16; ++i) {
;         const float g = acc[mi][0][i];
;         act[(size_t)EROW(rbase, i) * 2816 + n] = (h16)(g * sigmoidf_(g) * acc[mi][1][i]);
;       }
;     }
	v_exp_f32_e32 v185, v185
	v_add_u32_e32 v190, 0x2c000, v130
	v_add_u32_e32 v191, 0x2ec00, v130
	v_add_u32_e32 v192, 0x37000, v130
	v_add_u32_e32 v193, 0x39c00, v130
	v_add_f32_e32 v178, 1.0, v178
	v_add_f32_e32 v179, 1.0, v179
	v_add_f32_e32 v180, 1.0, v180
	v_add_f32_e32 v181, 1.0, v181
	v_add_f32_e32 v182, 1.0, v182
	v_add_f32_e32 v183, 1.0, v183
	v_add_f32_e32 v184, 1.0, v184
	v_add_f32_e32 v185, 1.0, v185
	v_rcp_f32_e32 v178, v178
	v_rcp_f32_e32 v179, v179
	v_rcp_f32_e32 v180, v180
	v_rcp_f32_e32 v181, v181
	v_rcp_f32_e32 v182, v182
	v_rcp_f32_e32 v183, v183
	v_rcp_f32_e32 v184, v184
	v_rcp_f32_e32 v185, v185
	v_mul_f32_e32 v178, v82, v178
	v_mul_f32_e32 v179, v83, v179
	v_mul_f32_e32 v180, v84, v180
	v_mul_f32_e32 v181, v85, v181
	v_mul_f32_e32 v182, v86, v182
	v_mul_f32_e32 v183, v87, v183
	v_mul_f32_e32 v184, v88, v184
	v_mul_f32_e32 v185, v89, v185
	v_fma_mixlo_f16 v178, v66, v178, 0
	v_fma_mixlo_f16 v180, v68, v180, 0
	v_fma_mixlo_f16 v182, v70, v182, 0
	v_fma_mixlo_f16 v184, v72, v184, 0
	v_fma_mixhi_f16 v178, v67, v179, 0
	v_fma_mixhi_f16 v180, v69, v181, 0
	v_fma_mixhi_f16 v182, v71, v183, 0
	v_fma_mixhi_f16 v184, v73, v185, 0
	v_mov_b32_dpp v186, v178 quad_perm:[1,0,3,2] row_mask:0xf bank_mask:0xf
	v_mov_b32_dpp v187, v180 quad_perm:[1,0,3,2] row_mask:0xf bank_mask:0xf
	v_mov_b32_dpp v188, v182 quad_perm:[1,0,3,2] row_mask:0xf bank_mask:0xf
	v_mov_b32_dpp v189, v184 quad_perm:[1,0,3,2] row_mask:0xf bank_mask:0xf
	v_perm_b32 v178, v186, v178, v194
	v_perm_b32 v180, v187, v180, v194
	v_perm_b32 v182, v188, v182, v194
	v_perm_b32 v184, v189, v184, v194
	global_store_dword v190, v178, s[8:9]
	global_store_dword v191, v180, s[8:9]
	global_store_dword v192, v182, s[8:9]
	global_store_dword v193, v184, s[8:9]
	v_mul_f32_e32 v178, 0xbfb8aa3b, v90
	v_mul_f32_e32 v179, 0xbfb8aa3b, v91
	v_mul_f32_e32 v180, 0xbfb8aa3b, v92
	v_mul_f32_e32 v181, 0xbfb8aa3b, v93
	v_mul_f32_e32 v182, 0xbfb8aa3b, v94
	v_mul_f32_e32 v183, 0xbfb8aa3b, v95
	v_mul_f32_e32 v184, 0xbfb8aa3b, v96
	v_mul_f32_e32 v185, 0xbfb8aa3b, v97
	v_exp_f32_e32 v178, v178
	v_exp_f32_e32 v179, v179
	v_exp_f32_e32 v180, v180
	v_exp_f32_e32 v181, v181
	v_exp_f32_e32 v182, v182
	v_exp_f32_e32 v183, v183
	v_exp_f32_e32 v184, v184
	v_exp_f32_e32 v185, v185
	v_add_u32_e32 v190, 0x42000, v130
	v_add_u32_e32 v191, 0x44c00, v130
	v_add_u32_e32 v192, 0x4d000, v130
	v_add_u32_e32 v193, 0x4fc00, v130
	v_add_f32_e32 v178, 1.0, v178
	v_add_f32_e32 v179, 1.0, v179
	v_add_f32_e32 v180, 1.0, v180
	v_add_f32_e32 v181, 1.0, v181
	v_add_f32_e32 v182, 1.0, v182
	v_add_f32_e32 v183, 1.0, v183
	v_add_f32_e32 v184, 1.0, v184
	v_add_f32_e32 v185, 1.0, v185
	v_rcp_f32_e32 v178, v178
	v_rcp_f32_e32 v179, v179
	v_rcp_f32_e32 v180, v180
	v_rcp_f32_e32 v181, v181
	v_rcp_f32_e32 v182, v182
	v_rcp_f32_e32 v183, v183
	v_rcp_f32_e32 v184, v184
	v_rcp_f32_e32 v185, v185
	v_mul_f32_e32 v178, v90, v178
	v_mul_f32_e32 v179, v91, v179
	v_mul_f32_e32 v180, v92, v180
	v_mul_f32_e32 v181, v93, v181
	v_mul_f32_e32 v182, v94, v182
	v_mul_f32_e32 v183, v95, v183
	v_mul_f32_e32 v184, v96, v184
	v_mul_f32_e32 v185, v97, v185
	v_fma_mixlo_f16 v178, v74, v178, 0
	v_fma_mixlo_f16 v180, v76, v180, 0
	v_fma_mixlo_f16 v182, v78, v182, 0
	v_fma_mixlo_f16 v184, v80, v184, 0
	v_fma_mixhi_f16 v178, v75, v179, 0
	v_fma_mixhi_f16 v180, v77, v181, 0
	v_fma_mixhi_f16 v182, v79, v183, 0
	v_fma_mixhi_f16 v184, v81, v185, 0
	v_mov_b32_dpp v186, v178 quad_perm:[1,0,3,2] row_mask:0xf bank_mask:0xf
	v_mov_b32_dpp v187, v180 quad_perm:[1,0,3,2] row_mask:0xf bank_mask:0xf
	v_mov_b32_dpp v188, v182 quad_perm:[1,0,3,2] row_mask:0xf bank_mask:0xf
	v_mov_b32_dpp v189, v184 quad_perm:[1,0,3,2] row_mask:0xf bank_mask:0xf
	v_perm_b32 v178, v186, v178, v194
	v_perm_b32 v180, v187, v180, v194
	v_perm_b32 v182, v188, v182, v194
	v_perm_b32 v184, v189, v184, v194
	global_store_dword v190, v178, s[8:9]
	global_store_dword v191, v180, s[8:9]
	global_store_dword v192, v182, s[8:9]
	global_store_dword v193, v184, s[8:9]
	v_mul_f32_e32 v178, 0xbfb8aa3b, v50
	v_mul_f32_e32 v179, 0xbfb8aa3b, v51
	v_mul_f32_e32 v180, 0xbfb8aa3b, v52
	v_mul_f32_e32 v181, 0xbfb8aa3b, v53
	v_mul_f32_e32 v182, 0xbfb8aa3b, v54
	v_mul_f32_e32 v183, 0xbfb8aa3b, v55
	v_mul_f32_e32 v184, 0xbfb8aa3b, v56
	v_mul_f32_e32 v185, 0xbfb8aa3b, v57
	v_exp_f32_e32 v178, v178
	v_exp_f32_e32 v179, v179
	v_exp_f32_e32 v180, v180
	v_exp_f32_e32 v181, v181
	v_exp_f32_e32 v182, v182
	v_exp_f32_e32 v183, v183
	v_exp_f32_e32 v184, v184
	v_exp_f32_e32 v185, v185
	v_add_u32_e32 v190, 0x58000, v130
	v_add_u32_e32 v191, 0x5ac00, v130
	v_add_u32_e32 v192, 0x63000, v130
	v_add_u32_e32 v193, 0x65c00, v130
	v_add_f32_e32 v178, 1.0, v178
	v_add_f32_e32 v179, 1.0, v179
	v_add_f32_e32 v180, 1.0, v180
	v_add_f32_e32 v181, 1.0, v181
	v_add_f32_e32 v182, 1.0, v182
	v_add_f32_e32 v183, 1.0, v183
	v_add_f32_e32 v184, 1.0, v184
	v_add_f32_e32 v185, 1.0, v185
	v_rcp_f32_e32 v178, v178
	v_rcp_f32_e32 v179, v179
	v_rcp_f32_e32 v180, v180
	v_rcp_f32_e32 v181, v181
	v_rcp_f32_e32 v182, v182
	v_rcp_f32_e32 v183, v183
	v_rcp_f32_e32 v184, v184
	v_rcp_f32_e32 v185, v185
	v_mul_f32_e32 v178, v50, v178
	v_mul_f32_e32 v179, v51, v179
	v_mul_f32_e32 v180, v52, v180
	v_mul_f32_e32 v181, v53, v181
	v_mul_f32_e32 v182, v54, v182
	v_mul_f32_e32 v183, v55, v183
	v_mul_f32_e32 v184, v56, v184
	v_mul_f32_e32 v185, v57, v185
	v_fma_mixlo_f16 v178, v34, v178, 0
	v_fma_mixlo_f16 v180, v36, v180, 0
	v_fma_mixlo_f16 v182, v38, v182, 0
	v_fma_mixlo_f16 v184, v40, v184, 0
	v_fma_mixhi_f16 v178, v35, v179, 0
	v_fma_mixhi_f16 v180, v37, v181, 0
	v_fma_mixhi_f16 v182, v39, v183, 0
	v_fma_mixhi_f16 v184, v41, v185, 0
; DI int TIDX() { int t = threadIdx.x; asm volatile("" : "+v"(t)); return t; }
; DI float sigmoidf_(float x) { return __builtin_amdgcn_rcpf(1.f + __expf(-x)); }
; DI void phase_ffn1(const P& p, int l, int hf, char* smem) {
;     ...
;     const int lane = TIDX() & 63, w = TIDX() >> 6, wm = w >> 1, wn = w & 1, hh = lane >> 5, c = lane & 31;
;     const int ml0 = m0 - mt0 * 128;
; #pragma unroll
;     for (int mi = 0; mi < 4; ++mi) {
;       const int rbase = ml0 + wm * 128 + mi * 32 + 4 * hh, n = c0 + wn * 32 + c;
; #pragma unroll
;       for (int i = 0; i < 16; ++i) {
;         const float g = acc[mi][0][i];
;         act[(size_t)EROW(rbase, i) * 2816 + n] = (h16)(g * sigmoidf_(g) * acc[mi][1][i]);
;       }
;     }
	v_mov_b32_dpp v186, v178 quad_perm:[1,0,3,2] row_mask:0xf bank_mask:0xf
	v_mov_b32_dpp v187, v180 quad_perm:[1,0,3,2] row_mask:0xf bank_mask:0xf
	v_mov_b32_dpp v188, v182 quad_perm:[1,0,3,2] row_mask:0xf bank_mask:0xf
	v_mov_b32_dpp v189, v184 quad_perm:[1,0,3,2] row_mask:0xf bank_mask:0xf
	v_perm_b32 v178, v186, v178, v194
	v_perm_b32 v180, v187, v180, v194
	v_perm_b32 v182, v188, v182, v194
	v_perm_b32 v184, v189, v184, v194
	global_store_dword v190, v178, s[8:9]
	global_store_dword v191, v180, s[8:9]
	global_store_dword v192, v182, s[8:9]
	global_store_dword v193, v184, s[8:9]
	v_mul_f32_e32 v178, 0xbfb8aa3b, v58
	v_mul_f32_e32 v179, 0xbfb8aa3b, v59
	v_mul_f32_e32 v180, 0xbfb8aa3b, v60
	v_mul_f32_e32 v181, 0xbfb8aa3b, v61
	v_mul_f32_e32 v182, 0xbfb8aa3b, v62
	v_mul_f32_e32 v183, 0xbfb8aa3b, v63
	v_mul_f32_e32 v184, 0xbfb8aa3b, v64
	v_mul_f32_e32 v185, 0xbfb8aa3b, v65
	v_exp_f32_e32 v178, v178
	v_exp_f32_e32 v179, v179
	v_exp_f32_e32 v180, v180
	v_exp_f32_e32 v181, v181
	v_exp_f32_e32 v182, v182
	v_exp_f32_e32 v183, v183
	v_exp_f32_e32 v184, v184
	v_exp_f32_e32 v185, v185
	v_add_u32_e32 v190, 0x6e000, v130
	v_add_u32_e32 v191, 0x70c00, v130
	v_add_u32_e32 v192, 0x79000, v130
	v_add_u32_e32 v193, 0x7bc00, v130
	v_add_f32_e32 v178, 1.0, v178
	v_add_f32_e32 v179, 1.0, v179
	v_add_f32_e32 v180, 1.0, v180
	v_add_f32_e32 v181, 1.0, v181
	v_add_f32_e32 v182, 1.0, v182
	v_add_f32_e32 v183, 1.0, v183
	v_add_f32_e32 v184, 1.0, v184
	v_add_f32_e32 v185, 1.0, v185
	v_rcp_f32_e32 v178, v178
	v_rcp_f32_e32 v179, v179
	v_rcp_f32_e32 v180, v180
	v_rcp_f32_e32 v181, v181
	v_rcp_f32_e32 v182, v182
	v_rcp_f32_e32 v183, v183
	v_rcp_f32_e32 v184, v184
	v_rcp_f32_e32 v185, v185
	v_mul_f32_e32 v178, v58, v178
	v_mul_f32_e32 v179, v59, v179
	v_mul_f32_e32 v180, v60, v180
	v_mul_f32_e32 v181, v61, v181
	v_mul_f32_e32 v182, v62, v182
	v_mul_f32_e32 v183, v63, v183
	v_mul_f32_e32 v184, v64, v184
	v_mul_f32_e32 v185, v65, v185
	v_fma_mixlo_f16 v178, v42, v178, 0
	v_fma_mixlo_f16 v180, v44, v180, 0
	v_fma_mixlo_f16 v182, v46, v182, 0
	v_fma_mixlo_f16 v184, v48, v184, 0
	v_fma_mixhi_f16 v178, v43, v179, 0
	v_fma_mixhi_f16 v180, v45, v181, 0
	v_fma_mixhi_f16 v182, v47, v183, 0
	v_fma_mixhi_f16 v184, v49, v185, 0
	v_mov_b32_dpp v186, v178 quad_perm:[1,0,3,2] row_mask:0xf bank_mask:0xf
	v_mov_b32_dpp v187, v180 quad_perm:[1,0,3,2] row_mask:0xf bank_mask:0xf
	v_mov_b32_dpp v188, v182 quad_perm:[1,0,3,2] row_mask:0xf bank_mask:0xf
	v_mov_b32_dpp v189, v184 quad_perm:[1,0,3,2] row_mask:0xf bank_mask:0xf
	v_perm_b32 v178, v186, v178, v194
	v_perm_b32 v180, v187, v180, v194
	v_perm_b32 v182, v188, v182, v194
	v_perm_b32 v184, v189, v184, v194
	global_store_dword v190, v178, s[8:9]
	global_store_dword v191, v180, s[8:9]
	global_store_dword v192, v182, s[8:9]
	global_store_dword v193, v184, s[8:9]
	v_mul_f32_e32 v178, 0xbfb8aa3b, v18
	v_mul_f32_e32 v179, 0xbfb8aa3b, v19
	v_mul_f32_e32 v180, 0xbfb8aa3b, v20
	v_mul_f32_e32 v181, 0xbfb8aa3b, v21
	v_mul_f32_e32 v182, 0xbfb8aa3b, v22
	v_mul_f32_e32 v183, 0xbfb8aa3b, v23
	v_mul_f32_e32 v184, 0xbfb8aa3b, v24
	v_mul_f32_e32 v185, 0xbfb8aa3b, v25
	v_exp_f32_e32 v178, v178
	v_exp_f32_e32 v179, v179
	v_exp_f32_e32 v180, v180
	v_exp_f32_e32 v181, v181
	v_exp_f32_e32 v182, v182
	v_exp_f32_e32 v183, v183
	v_exp_f32_e32 v184, v184
	v_exp_f32_e32 v185, v185
	v_add_u32_e32 v190, 0x84000, v130
	v_add_u32_e32 v191, 0x86c00, v130
	v_add_u32_e32 v192, 0x8f000, v130
	v_add_u32_e32 v193, 0x91c00, v130
	v_add_f32_e32 v178, 1.0, v178
	v_add_f32_e32 v179, 1.0, v179
	v_add_f32_e32 v180, 1.0, v180
	v_add_f32_e32 v181, 1.0, v181
	v_add_f32_e32 v182, 1.0, v182
; DI int TIDX() { int t = threadIdx.x; asm volatile("" : "+v"(t)); return t; }
; DI float sigmoidf_(float x) { return __builtin_amdgcn_rcpf(1.f + __expf(-x)); }
; DI void phase_ffn1(const P& p, int l, int hf, char* smem) {
;     ...
;     const int lane = TIDX() & 63, w = TIDX() >> 6, wm = w >> 1, wn = w & 1, hh = lane >> 5, c = lane & 31;
;     const int ml0 = m0 - mt0 * 128;
; #pragma unroll
;     for (int mi = 0; mi < 4; ++mi) {
;       const int rbase = ml0 + wm * 128 + mi * 32 + 4 * hh, n = c0 + wn * 32 + c;
; #pragma unroll
;       for (int i = 0; i < 16; ++i) {
;         const float g = acc[mi][0][i];
;         act[(size_t)EROW(rbase, i) * 2816 + n] = (h16)(g * sigmoidf_(g) * acc[mi][1][i]);
;       }
;     }
	v_add_f32_e32 v183, 1.0, v183
	v_add_f32_e32 v184, 1.0, v184
	v_add_f32_e32 v185, 1.0, v185
	v_rcp_f32_e32 v178, v178
	v_rcp_f32_e32 v179, v179
	v_rcp_f32_e32 v180, v180
	v_rcp_f32_e32 v181, v181
	v_rcp_f32_e32 v182, v182
	v_rcp_f32_e32 v183, v183
	v_rcp_f32_e32 v184, v184
	v_rcp_f32_e32 v185, v185
	v_mul_f32_e32 v178, v18, v178
	v_mul_f32_e32 v179, v19, v179
	v_mul_f32_e32 v180, v20, v180
	v_mul_f32_e32 v181, v21, v181
	v_mul_f32_e32 v182, v22, v182
	v_mul_f32_e32 v183, v23, v183
	v_mul_f32_e32 v184, v24, v184
	v_mul_f32_e32 v185, v25, v185
	v_fma_mixlo_f16 v178, v2, v178, 0
	v_fma_mixlo_f16 v180, v4, v180, 0
	v_fma_mixlo_f16 v182, v6, v182, 0
	v_fma_mixlo_f16 v184, v8, v184, 0
	v_fma_mixhi_f16 v178, v3, v179, 0
	v_fma_mixhi_f16 v180, v5, v181, 0
	v_fma_mixhi_f16 v182, v7, v183, 0
	v_fma_mixhi_f16 v184, v9, v185, 0
	v_mov_b32_dpp v186, v178 quad_perm:[1,0,3,2] row_mask:0xf bank_mask:0xf
	v_mov_b32_dpp v187, v180 quad_perm:[1,0,3,2] row_mask:0xf bank_mask:0xf
	v_mov_b32_dpp v188, v182 quad_perm:[1,0,3,2] row_mask:0xf bank_mask:0xf
	v_mov_b32_dpp v189, v184 quad_perm:[1,0,3,2] row_mask:0xf bank_mask:0xf
	v_perm_b32 v178, v186, v178, v194
	v_perm_b32 v180, v187, v180, v194
	v_perm_b32 v182, v188, v182, v194
	v_perm_b32 v184, v189, v184, v194
	global_store_dword v190, v178, s[8:9]
	global_store_dword v191, v180, s[8:9]
	global_store_dword v192, v182, s[8:9]
	global_store_dword v193, v184, s[8:9]
	v_mul_f32_e32 v178, 0xbfb8aa3b, v26
	v_mul_f32_e32 v179, 0xbfb8aa3b, v27
	v_mul_f32_e32 v180, 0xbfb8aa3b, v28
	v_mul_f32_e32 v181, 0xbfb8aa3b, v29
	v_mul_f32_e32 v182, 0xbfb8aa3b, v30
	v_mul_f32_e32 v183, 0xbfb8aa3b, v31
	v_mul_f32_e32 v184, 0xbfb8aa3b, v32
	v_mul_f32_e32 v185, 0xbfb8aa3b, v33
	v_exp_f32_e32 v178, v178
	v_exp_f32_e32 v179, v179
	v_exp_f32_e32 v180, v180
	v_exp_f32_e32 v181, v181
	v_exp_f32_e32 v182, v182
	v_exp_f32_e32 v183, v183
	v_exp_f32_e32 v184, v184
	v_exp_f32_e32 v185, v185
	v_add_u32_e32 v190, 0x9a000, v130
	v_add_u32_e32 v191, 0x9cc00, v130
	v_add_u32_e32 v192, 0xa5000, v130
	v_add_u32_e32 v193, 0xa7c00, v130
	v_add_f32_e32 v178, 1.0, v178
	v_add_f32_e32 v179, 1.0, v179
	v_add_f32_e32 v180, 1.0, v180
	v_add_f32_e32 v181, 1.0, v181
	v_add_f32_e32 v182, 1.0, v182
	v_add_f32_e32 v183, 1.0, v183
	v_add_f32_e32 v184, 1.0, v184
	v_add_f32_e32 v185, 1.0, v185
	v_rcp_f32_e32 v178, v178
	v_rcp_f32_e32 v179, v179
	v_rcp_f32_e32 v180, v180
	v_rcp_f32_e32 v181, v181
	v_rcp_f32_e32 v182, v182
	v_rcp_f32_e32 v183, v183
	v_rcp_f32_e32 v184, v184
	v_rcp_f32_e32 v185, v185
	v_mul_f32_e32 v178, v26, v178
	v_mul_f32_e32 v179, v27, v179
	v_mul_f32_e32 v180, v28, v180
	v_mul_f32_e32 v181, v29, v181
	v_mul_f32_e32 v182, v30, v182
	v_mul_f32_e32 v183, v31, v183
	v_mul_f32_e32 v184, v32, v184
	v_mul_f32_e32 v185, v33, v185
	v_fma_mixlo_f16 v178, v10, v178, 0
	v_fma_mixlo_f16 v180, v12, v180, 0
	v_fma_mixlo_f16 v182, v14, v182, 0
	v_fma_mixlo_f16 v184, v16, v184, 0
	v_fma_mixhi_f16 v178, v11, v179, 0
	v_fma_mixhi_f16 v180, v13, v181, 0
	v_fma_mixhi_f16 v182, v15, v183, 0
	v_fma_mixhi_f16 v184, v17, v185, 0
	v_mov_b32_dpp v186, v178 quad_perm:[1,0,3,2] row_mask:0xf bank_mask:0xf
	v_mov_b32_dpp v187, v180 quad_perm:[1,0,3,2] row_mask:0xf bank_mask:0xf
	v_mov_b32_dpp v188, v182 quad_perm:[1,0,3,2] row_mask:0xf bank_mask:0xf
	v_mov_b32_dpp v189, v184 quad_perm:[1,0,3,2] row_mask:0xf bank_mask:0xf
	v_perm_b32 v178, v186, v178, v194
	v_perm_b32 v180, v187, v180, v194
	v_perm_b32 v182, v188, v182, v194
	v_perm_b32 v184, v189, v184, v194
	global_store_dword v190, v178, s[8:9]
	global_store_dword v191, v180, s[8:9]
	global_store_dword v192, v182, s[8:9]
	global_store_dword v193, v184, s[8:9]
